# SSD chunk loop: off-diagonal sub-blocks sb=0/1 use a mask-free decay chain (no readlane pairs / cndmask) selected per wave
# speedup vs baseline: 1.0017x; 1.0017x over previous
; #define LAS __attribute__((address_space(3)))
; __device__ __forceinline__ int opaque_tid() { int t = threadIdx.x; asm volatile("" : "+v"(t)); return t; }
; __device__ __forceinline__ void seq_of(int sq, int& start, int& len) { if (sq < 4) { start = sq * 2048; len = 2048; } else { start = TP + (sq - 4) * 4096; len = 4096; } }
; __device__ __forceinline__ void ssd_item(CP& P, int L, int sq, int hd, int dir, LAS unsigned char* lds) {
;     const int tid = opaque_tid(), lane = tid & 63, wid = __builtin_amdgcn_readfirstlane(tid >> 6), r = lane & 31, hi = lane >> 5;
;     int sstart, slen; seq_of(sq, sstart, slen); const int nc = slen / 128, g = hd / 6;
;     const bf16_t* xbc = (const bf16_t*)(P.ws + WS_XBC); const float* DT = (const float*)(P.ws + WS_DT);
;     bf16_t* Y = (bf16_t*)(P.ws + (dir ? WS_YB : WS_YF));
;     const float Aneg = -__expf(P.in[I_ALOG][L * 24 + dir * 12 + hd]), dtb = P.in[I_DTB][L * 24 + dir * 12 + hd]; const int dcol = dir * 12 + hd;
;     LAS float* AS = (LAS float*)(lds + S_AS); LAS float* DTV = (LAS float*)(lds + S_DTV);
;     f32x16 st;
; #pragma unroll
;     for (int i = 0; i < 16; ++i) st[i] = 0.f;
;     for (int i = tid; i < 64 * SP / 4; i += 512) ((LAS unsigned*)(lds + S_PV))[i] = 0u;
.LBB0_86:
	s_bfe_i32 s0, s8, 0x80000
	s_mul_i32 s0, s0, 43
	s_sext_i32_i16 s1, s0
	s_ashr_i32 s1, s1, 9
	s_bfe_u32 s0, s0, 0x1000f
	s_add_i32 s0, s1, s0
	s_mul_i32 s0, s0, 12
	s_sub_i32 s9, s8, s0
	v_mov_b32_e32 v5, v195
	s_sext_i32_i8 s1, s9
	s_load_dwordx4 s[4:7], s[64:65], 0x60
	s_sext_i32_i8 s0, s0
	s_add_i32 s0, s0, s1
	s_mul_i32 s10, s28, 24
	s_add_i32 s10, s0, s10
	s_ashr_i32 s11, s10, 31
	s_lshl_b64 s[10:11], s[10:11], 2
	s_waitcnt lgkmcnt(0)
	s_add_u32 s6, s6, s10
	s_addc_u32 s7, s7, s11
	s_add_u32 s4, s4, s10
	s_addc_u32 s5, s5, s11
	global_load_dword v6, v193, s[6:7]
	global_load_dword v104, v193, s[4:5]
	s_movk_i32 s4, 0x1100
	v_readfirstlane_b32 s14, v5
	s_lshr_b32 s32, s14, 7
	v_cmp_gt_i32_e32 vcc, s4, v5
	s_and_saveexec_b64 s[4:5], vcc
	s_cbranch_execz .LBB0_89
	v_readlane_b32 s6, v252, 61
	v_add_u32_e32 v0, 0xfffffe00, v5
	s_nop 0
	v_lshl_add_u32 v1, v5, 2, s6
	s_mov_b64 s[6:7], 0

; #define LAS __attribute__((address_space(3)))
; #define MFMA32(a, b, c) __builtin_amdgcn_mfma_f32_32x32x16_bf16((a), (b), (c), 0, 0, 0)
; __device__ __forceinline__ int crow(int r, int hi) { return (r & 3) + 8 * (r >> 2) + 4 * hi; }
; __device__ __forceinline__ void ssd_item(CP& P, int L, int sq, int hd, int dir, LAS unsigned char* lds) {
;     ...
;             for (int sb = 0; sb < 4; ++sb) if (sb >= sb0 && sb < sb1) {
;                 f32x16 cb;
; #pragma unroll
;                 for (int i = 0; i < 16; ++i) cb[i] = 0.f;
; #pragma unroll
;                 for (int ks = 0; ks < 8; ++ks) { const bf16x8 av = *(const LAS bf16x8*)(lds + S_BM + (32 * sb + r) * SP + (16 * ks + 8 * hi) * 2);
;                     const bf16x8 bv2 = *(const LAS bf16x8*)(lds + S_CM + lrow * SP + (16 * ks + 8 * hi) * 2); cb = MFMA32(av, bv2, cb); }
; #pragma unroll
;                 for (int i = 0; i < 16; ++i) { const int sr = 32 * sb + crow(i, hi); const bool ok = dir ? (sr >= lrow) : (sr <= lrow); const float gv = cb[i] * __expf(a_l - AS[sr]); cb[i] = ok ? gv : 0.f; }
; #pragma unroll
;                 for (int s2 = 0; s2 < 2; ++s2) { const LAS unsigned char* xp = lds + S_XD + (32 * sb + 16 * s2 + 4 * hi + trq) * SXP + 64 * pb + trb;
;                     const s16x4 lo = __builtin_bit_cast(s16x4, __builtin_amdgcn_ds_read_tr16_b64_v4i16((LAS v4i16s_t*)xp));
;                     const s16x4 hi4 = __builtin_bit_cast(s16x4, __builtin_amdgcn_ds_read_tr16_b64_v4i16((LAS v4i16s_t*)(xp + 8 * SXP)));
;                     const bf16x8 xa = __builtin_shufflevector(lo, hi4, 0, 1, 2, 3, 4, 5, 6, 7);
;                     yd = MFMA32(xa, pack_step(cb, s2), yd); }
.LBB0_106:
	s_waitcnt lgkmcnt(0)
	s_barrier
	ds_read_b32 v103, v109
	s_andn2_b64 vcc, exec, s[4:5]
	s_cbranch_vccnz .LBB0_108
	ds_read_b128 v[200:203], v151 offset:34816
	ds_read_b128 v[208:211], v152
	ds_read_b128 v[212:215], v151 offset:34848
	ds_read_b128 v[216:219], v152 offset:32
	ds_read_b128 v[220:223], v151 offset:34880
	ds_read_b128 v[246:249], v152 offset:64
	ds_read_b128 v[32:35], v151 offset:34912
	ds_read_b128 v[36:39], v152 offset:96
	v_readlane_b32 s20, v254, 13
	v_readlane_b32 s21, v254, 14
	s_waitcnt lgkmcnt(6)
	v_mfma_f32_32x32x16_bf16 v[16:31], v[200:203], v[208:211], 0
	ds_read_b128 v[200:203], v151 offset:34944
	ds_read_b128 v[208:211], v152 offset:128
	s_waitcnt lgkmcnt(6)
	v_mfma_f32_32x32x16_bf16 v[16:31], v[212:215], v[216:219], v[16:31]
	ds_read_b128 v[212:215], v151 offset:34976
	ds_read_b128 v[216:219], v152 offset:160
	s_waitcnt lgkmcnt(6)
	v_mfma_f32_32x32x16_bf16 v[16:31], v[220:223], v[246:249], v[16:31]
	ds_read_b128 v[220:223], v151 offset:35008
	ds_read_b128 v[246:249], v152 offset:192
	s_waitcnt lgkmcnt(6)
	v_mfma_f32_32x32x16_bf16 v[16:31], v[32:35], v[36:39], v[16:31]
	ds_read_b128 v[32:35], v151 offset:35040
	ds_read_b128 v[36:39], v152 offset:224
	s_waitcnt lgkmcnt(6)
	v_mfma_f32_32x32x16_bf16 v[16:31], v[200:203], v[208:211], v[16:31]
	s_waitcnt lgkmcnt(4)
	v_mfma_f32_32x32x16_bf16 v[16:31], v[212:215], v[216:219], v[16:31]
	s_waitcnt lgkmcnt(2)
	v_mfma_f32_32x32x16_bf16 v[16:31], v[220:223], v[246:249], v[16:31]
	s_waitcnt lgkmcnt(0)
	v_mfma_f32_32x32x16_bf16 v[16:31], v[32:35], v[36:39], v[16:31]
	s_cmp_lg_u32 s32, 0
	s_cbranch_scc1 .Lssd_nm0
	ds_read_b128 v[32:35], v123
	s_waitcnt lgkmcnt(0)
	v_sub_f32_e32 v32, v103, v32
	v_mul_f32_e32 v32, 0x3fb8aa3b, v32
	v_exp_f32_e32 v32, v32
	s_nop 6
	v_mul_f32_e32 v16, v16, v32
	v_cndmask_b32_e64 v32, 0, v16, s[20:21]
	v_sub_f32_e32 v16, v103, v33
	v_mul_f32_e32 v16, 0x3fb8aa3b, v16
	v_exp_f32_e32 v16, v16
	v_readlane_b32 s20, v254, 15
	v_readlane_b32 s21, v254, 16
	v_mul_f32_e32 v16, v17, v16
	s_nop 0
	v_cndmask_b32_e64 v33, 0, v16, s[20:21]
	v_sub_f32_e32 v16, v103, v34
	v_mul_f32_e32 v16, 0x3fb8aa3b, v16
	v_exp_f32_e32 v16, v16
	v_readlane_b32 s20, v254, 17
	v_readlane_b32 s21, v254, 18
	v_mul_f32_e32 v16, v18, v16
	s_nop 0
	v_cndmask_b32_e64 v34, 0, v16, s[20:21]
	v_sub_f32_e32 v16, v103, v35
	v_mul_f32_e32 v16, 0x3fb8aa3b, v16
	v_exp_f32_e32 v16, v16
	v_readlane_b32 s20, v254, 19
	v_readlane_b32 s21, v254, 20
	v_mul_f32_e32 v16, v19, v16
	s_nop 0
	v_cndmask_b32_e64 v35, 0, v16, s[20:21]
	ds_read_b128 v[16:19], v124
	v_readlane_b32 s20, v254, 21
	v_readlane_b32 s21, v254, 22
	s_waitcnt lgkmcnt(0)
	v_sub_f32_e32 v16, v103, v16
	v_mul_f32_e32 v16, 0x3fb8aa3b, v16
	v_exp_f32_e32 v16, v16
	s_nop 0
	v_mul_f32_e32 v16, v20, v16
	v_cndmask_b32_e64 v20, 0, v16, s[20:21]
	v_sub_f32_e32 v16, v103, v17
	v_mul_f32_e32 v16, 0x3fb8aa3b, v16
	v_exp_f32_e32 v16, v16
	v_readlane_b32 s20, v254, 23
	v_readlane_b32 s21, v254, 24
	v_mul_f32_e32 v16, v21, v16
	s_nop 0
	v_cndmask_b32_e64 v21, 0, v16, s[20:21]
	v_sub_f32_e32 v16, v103, v18
	v_mul_f32_e32 v16, 0x3fb8aa3b, v16
	v_exp_f32_e32 v16, v16
	v_readlane_b32 s20, v254, 25
	v_readlane_b32 s21, v254, 26
	v_mul_f32_e32 v16, v22, v16
	s_nop 0
	v_cndmask_b32_e64 v22, 0, v16, s[20:21]
	v_sub_f32_e32 v16, v103, v19
	v_mul_f32_e32 v16, 0x3fb8aa3b, v16
	v_exp_f32_e32 v16, v16
	v_readlane_b32 s20, v254, 27
	v_readlane_b32 s21, v254, 28
	v_mul_f32_e32 v16, v23, v16
	s_nop 0
	v_cndmask_b32_e64 v23, 0, v16, s[20:21]
	ds_read_b128 v[16:19], v125
	v_readlane_b32 s20, v254, 29
	v_readlane_b32 s21, v254, 30
	s_waitcnt lgkmcnt(0)
	v_sub_f32_e32 v16, v103, v16
	v_mul_f32_e32 v16, 0x3fb8aa3b, v16
	v_exp_f32_e32 v16, v16
	s_nop 0
	v_mul_f32_e32 v16, v24, v16
	v_cndmask_b32_e64 v36, 0, v16, s[20:21]
	v_sub_f32_e32 v16, v103, v17
	v_mul_f32_e32 v16, 0x3fb8aa3b, v16
	v_exp_f32_e32 v16, v16
	v_readlane_b32 s20, v254, 31
	v_readlane_b32 s21, v254, 32
	v_cvt_pk_bf16_f32 v24, v32, v33
	v_mul_f32_e32 v16, v25, v16
	v_cndmask_b32_e64 v37, 0, v16, s[20:21]
	v_sub_f32_e32 v16, v103, v18
	v_mul_f32_e32 v16, 0x3fb8aa3b, v16
	v_exp_f32_e32 v16, v16
	v_readlane_b32 s20, v254, 33
	v_readlane_b32 s21, v254, 34
	v_cvt_pk_bf16_f32 v25, v34, v35
	v_mul_f32_e32 v16, v26, v16
	v_cndmask_b32_e64 v38, 0, v16, s[20:21]
	v_sub_f32_e32 v16, v103, v19
	v_mul_f32_e32 v16, 0x3fb8aa3b, v16
	v_exp_f32_e32 v16, v16
	v_readlane_b32 s20, v254, 35
	v_readlane_b32 s21, v254, 36
	v_cvt_pk_bf16_f32 v26, v20, v21
	v_mul_f32_e32 v16, v27, v16
	v_cndmask_b32_e64 v39, 0, v16, s[20:21]
	ds_read_b128 v[16:19], v127
	v_readlane_b32 s20, v254, 37
	v_readlane_b32 s21, v254, 38
	v_cvt_pk_bf16_f32 v27, v22, v23
	v_cvt_pk_bf16_f32 v36, v36, v37
	s_waitcnt lgkmcnt(0)
	v_sub_f32_e32 v16, v103, v16
	v_mul_f32_e32 v16, 0x3fb8aa3b, v16
	v_exp_f32_e32 v16, v16
	v_cvt_pk_bf16_f32 v37, v38, v39
	v_mul_f32_e32 v16, v28, v16
	v_cndmask_b32_e64 v40, 0, v16, s[20:21]
	v_sub_f32_e32 v16, v103, v17
	v_mul_f32_e32 v16, 0x3fb8aa3b, v16
	v_exp_f32_e32 v16, v16
	v_readlane_b32 s20, v254, 39
	v_readlane_b32 s21, v254, 40
	v_mul_f32_e32 v16, v29, v16
	s_nop 0
	v_cndmask_b32_e64 v41, 0, v16, s[20:21]
	v_sub_f32_e32 v16, v103, v18
	v_mul_f32_e32 v16, 0x3fb8aa3b, v16
	v_exp_f32_e32 v16, v16
	v_readlane_b32 s20, v254, 41
	v_readlane_b32 s21, v254, 42
	v_cvt_pk_bf16_f32 v38, v40, v41
	v_mul_f32_e32 v16, v30, v16
	v_cndmask_b32_e64 v42, 0, v16, s[20:21]
	v_sub_f32_e32 v16, v103, v19
	v_mul_f32_e32 v16, 0x3fb8aa3b, v16
	v_exp_f32_e32 v16, v16
	v_readlane_b32 s20, v254, 43
	v_readlane_b32 s21, v254, 44
	v_mul_f32_e32 v16, v31, v16
	s_nop 0
	v_cndmask_b32_e64 v43, 0, v16, s[20:21]
	ds_read_b64_tr_b16 v[16:17], v143
	ds_read_b64_tr_b16 v[18:19], v143 offset:1152
	s_waitcnt lgkmcnt(0)
	v_mfma_f32_32x32x16_bf16 v[16:31], v[16:19], v[24:27], 0
	ds_read_b64_tr_b16 v[32:33], v143 offset:2304
	ds_read_b64_tr_b16 v[34:35], v143 offset:3456
	v_cvt_pk_bf16_f32 v39, v42, v43
	s_waitcnt lgkmcnt(0)
	s_nop 0
	v_mfma_f32_32x32x16_bf16 v[16:31], v[32:35], v[36:39], v[16:31]
	s_andn2_b64 vcc, exec, s[14:15]
	s_cbranch_vccz .LBB0_109
	s_branch .LBB0_110
; #define LAS __attribute__((address_space(3)))
; #define MFMA32(a, b, c) __builtin_amdgcn_mfma_f32_32x32x16_bf16((a), (b), (c), 0, 0, 0)
; __device__ __forceinline__ int crow(int r, int hi) { return (r & 3) + 8 * (r >> 2) + 4 * hi; }
; __device__ __forceinline__ void ssd_item(CP& P, int L, int sq, int hd, int dir, LAS unsigned char* lds) {
;     ...
; #pragma unroll
;                 for (int i = 0; i < 16; ++i) { const int sr = 32 * sb + crow(i, hi); const bool ok = dir ? (sr >= lrow) : (sr <= lrow); const float gv = cb[i] * __expf(a_l - AS[sr]); cb[i] = ok ? gv : 0.f; }
; #pragma unroll
;                 for (int s2 = 0; s2 < 2; ++s2) { const LAS unsigned char* xp = lds + S_XD + (32 * sb + 16 * s2 + 4 * hi + trq) * SXP + 64 * pb + trb;
;                     const s16x4 lo = __builtin_bit_cast(s16x4, __builtin_amdgcn_ds_read_tr16_b64_v4i16((LAS v4i16s_t*)xp));
;                     const s16x4 hi4 = __builtin_bit_cast(s16x4, __builtin_amdgcn_ds_read_tr16_b64_v4i16((LAS v4i16s_t*)(xp + 8 * SXP)));
;                     const bf16x8 xa = __builtin_shufflevector(lo, hi4, 0, 1, 2, 3, 4, 5, 6, 7);
;                     yd = MFMA32(xa, pack_step(cb, s2), yd); }
.Lssd_nm0:
	ds_read_b128 v[32:35], v123
	s_waitcnt lgkmcnt(0)
	v_sub_f32_e32 v32, v103, v32
	v_mul_f32_e32 v32, 0x3fb8aa3b, v32
	v_exp_f32_e32 v32, v32
	s_nop 6
	v_mul_f32_e32 v32, v16, v32
	v_sub_f32_e32 v16, v103, v33
	v_mul_f32_e32 v16, 0x3fb8aa3b, v16
	v_exp_f32_e32 v16, v16
	s_nop 0
	v_mul_f32_e32 v33, v17, v16
	v_sub_f32_e32 v16, v103, v34
	v_mul_f32_e32 v16, 0x3fb8aa3b, v16
	v_exp_f32_e32 v16, v16
	s_nop 0
	v_mul_f32_e32 v34, v18, v16
	v_sub_f32_e32 v16, v103, v35
	v_mul_f32_e32 v16, 0x3fb8aa3b, v16
	v_exp_f32_e32 v16, v16
	s_nop 0
	v_mul_f32_e32 v35, v19, v16
	ds_read_b128 v[16:19], v124
	s_waitcnt lgkmcnt(0)
	v_sub_f32_e32 v16, v103, v16
	v_mul_f32_e32 v16, 0x3fb8aa3b, v16
	v_exp_f32_e32 v16, v16
	s_nop 0
	v_mul_f32_e32 v20, v20, v16
	v_sub_f32_e32 v16, v103, v17
	v_mul_f32_e32 v16, 0x3fb8aa3b, v16
	v_exp_f32_e32 v16, v16
	s_nop 0
	v_mul_f32_e32 v21, v21, v16
	v_sub_f32_e32 v16, v103, v18
	v_mul_f32_e32 v16, 0x3fb8aa3b, v16
	v_exp_f32_e32 v16, v16
	s_nop 0
	v_mul_f32_e32 v22, v22, v16
	v_sub_f32_e32 v16, v103, v19
	v_mul_f32_e32 v16, 0x3fb8aa3b, v16
	v_exp_f32_e32 v16, v16
	s_nop 0
	v_mul_f32_e32 v23, v23, v16
	ds_read_b128 v[16:19], v125
	s_waitcnt lgkmcnt(0)
	v_sub_f32_e32 v16, v103, v16
	v_mul_f32_e32 v16, 0x3fb8aa3b, v16
	v_exp_f32_e32 v16, v16
	s_nop 0
	v_mul_f32_e32 v36, v24, v16
	v_sub_f32_e32 v16, v103, v17
	v_mul_f32_e32 v16, 0x3fb8aa3b, v16
	v_exp_f32_e32 v16, v16
	v_cvt_pk_bf16_f32 v24, v32, v33
	v_mul_f32_e32 v37, v25, v16
	v_sub_f32_e32 v16, v103, v18
	v_mul_f32_e32 v16, 0x3fb8aa3b, v16
	v_exp_f32_e32 v16, v16
	v_cvt_pk_bf16_f32 v25, v34, v35
	v_mul_f32_e32 v38, v26, v16
	v_sub_f32_e32 v16, v103, v19
	v_mul_f32_e32 v16, 0x3fb8aa3b, v16
	v_exp_f32_e32 v16, v16
	v_cvt_pk_bf16_f32 v26, v20, v21
	v_mul_f32_e32 v39, v27, v16
	ds_read_b128 v[16:19], v127
	v_cvt_pk_bf16_f32 v27, v22, v23
	v_cvt_pk_bf16_f32 v36, v36, v37
	s_waitcnt lgkmcnt(0)
	v_sub_f32_e32 v16, v103, v16
	v_mul_f32_e32 v16, 0x3fb8aa3b, v16
	v_exp_f32_e32 v16, v16
	v_cvt_pk_bf16_f32 v37, v38, v39
	v_mul_f32_e32 v40, v28, v16
	v_sub_f32_e32 v16, v103, v17
	v_mul_f32_e32 v16, 0x3fb8aa3b, v16
	v_exp_f32_e32 v16, v16
	s_nop 0
	v_mul_f32_e32 v41, v29, v16
	v_sub_f32_e32 v16, v103, v18
	v_mul_f32_e32 v16, 0x3fb8aa3b, v16
	v_exp_f32_e32 v16, v16
	v_cvt_pk_bf16_f32 v38, v40, v41
	v_mul_f32_e32 v42, v30, v16
	v_sub_f32_e32 v16, v103, v19
	v_mul_f32_e32 v16, 0x3fb8aa3b, v16
	v_exp_f32_e32 v16, v16
	s_nop 0
	v_mul_f32_e32 v43, v31, v16
	ds_read_b64_tr_b16 v[16:17], v143
	ds_read_b64_tr_b16 v[18:19], v143 offset:1152
	s_waitcnt lgkmcnt(0)
	v_mfma_f32_32x32x16_bf16 v[16:31], v[16:19], v[24:27], 0
	ds_read_b64_tr_b16 v[32:33], v143 offset:2304
	ds_read_b64_tr_b16 v[34:35], v143 offset:3456
	v_cvt_pk_bf16_f32 v39, v42, v43
	s_waitcnt lgkmcnt(0)
	s_nop 0
	v_mfma_f32_32x32x16_bf16 v[16:31], v[32:35], v[36:39], v[16:31]
	s_andn2_b64 vcc, exec, s[14:15]
	s_cbranch_vccz .LBB0_109
	s_branch .LBB0_110
.Lssd_nm1:
	ds_read_b128 v[154:157], v128
	s_waitcnt lgkmcnt(0)
	v_sub_f32_e32 v153, v103, v154
	v_mul_f32_e32 v153, 0x3fb8aa3b, v153
	v_exp_f32_e32 v153, v153
	s_nop 6
	v_mul_f32_e32 v153, v32, v153
	v_sub_f32_e32 v32, v103, v155
	v_mul_f32_e32 v32, 0x3fb8aa3b, v32
	v_exp_f32_e32 v32, v32
	s_nop 0
	v_mul_f32_e32 v154, v33, v32
	v_sub_f32_e32 v32, v103, v156
	v_mul_f32_e32 v32, 0x3fb8aa3b, v32
	v_exp_f32_e32 v32, v32
	s_nop 0
	v_mul_f32_e32 v155, v34, v32
	v_sub_f32_e32 v32, v103, v157
	v_mul_f32_e32 v32, 0x3fb8aa3b, v32
	v_exp_f32_e32 v32, v32
	s_nop 0
	v_mul_f32_e32 v156, v35, v32
	ds_read_b128 v[32:35], v129
	s_waitcnt lgkmcnt(0)
	v_sub_f32_e32 v32, v103, v32
	v_mul_f32_e32 v32, 0x3fb8aa3b, v32
	v_exp_f32_e32 v32, v32
	s_nop 0
	v_mul_f32_e32 v36, v36, v32
	v_sub_f32_e32 v32, v103, v33
	v_mul_f32_e32 v32, 0x3fb8aa3b, v32
	v_exp_f32_e32 v32, v32
	s_nop 0
	v_mul_f32_e32 v37, v37, v32
	v_sub_f32_e32 v32, v103, v34
	v_mul_f32_e32 v32, 0x3fb8aa3b, v32
	v_exp_f32_e32 v32, v32
	s_nop 0
	v_mul_f32_e32 v38, v38, v32
	v_sub_f32_e32 v32, v103, v35
	v_mul_f32_e32 v32, 0x3fb8aa3b, v32
	v_exp_f32_e32 v32, v32
	s_nop 0
	v_mul_f32_e32 v39, v39, v32
	ds_read_b128 v[32:35], v130
	s_waitcnt lgkmcnt(0)
	v_sub_f32_e32 v32, v103, v32
	v_mul_f32_e32 v32, 0x3fb8aa3b, v32
	v_exp_f32_e32 v32, v32
	s_nop 0
	v_mul_f32_e32 v157, v40, v32
	v_sub_f32_e32 v32, v103, v33
	v_mul_f32_e32 v32, 0x3fb8aa3b, v32
	v_exp_f32_e32 v32, v32
	v_readlane_b32 s21, v255, 0
	v_cvt_pk_bf16_f32 v40, v153, v154
	v_mul_f32_e32 v158, v41, v32
	v_sub_f32_e32 v32, v103, v34
	v_mul_f32_e32 v32, 0x3fb8aa3b, v32
	v_exp_f32_e32 v32, v32
	v_readlane_b32 s20, v255, 1
	v_readlane_b32 s21, v255, 2
	v_cvt_pk_bf16_f32 v41, v155, v156
	v_mul_f32_e32 v159, v42, v32
	v_sub_f32_e32 v32, v103, v35
	v_mul_f32_e32 v32, 0x3fb8aa3b, v32
	v_exp_f32_e32 v32, v32
	v_readlane_b32 s20, v255, 3
	v_readlane_b32 s21, v255, 4
	v_cvt_pk_bf16_f32 v42, v36, v37
	v_mul_f32_e32 v160, v43, v32
	ds_read_b128 v[32:35], v131
	v_readlane_b32 s20, v255, 5
	v_readlane_b32 s21, v255, 6
	v_cvt_pk_bf16_f32 v43, v38, v39
	v_cvt_pk_bf16_f32 v36, v157, v158
	s_waitcnt lgkmcnt(0)
	v_sub_f32_e32 v32, v103, v32
	v_mul_f32_e32 v32, 0x3fb8aa3b, v32
	v_exp_f32_e32 v32, v32
	v_cvt_pk_bf16_f32 v37, v159, v160
	v_mul_f32_e32 v44, v44, v32
	v_sub_f32_e32 v32, v103, v33
	v_mul_f32_e32 v32, 0x3fb8aa3b, v32
	v_exp_f32_e32 v32, v32
	v_readlane_b32 s20, v255, 7
	v_readlane_b32 s21, v255, 8
	s_nop 0
	v_mul_f32_e32 v45, v45, v32
	v_sub_f32_e32 v32, v103, v34
	v_mul_f32_e32 v32, 0x3fb8aa3b, v32
	v_exp_f32_e32 v32, v32
	v_readlane_b32 s20, v255, 9
	v_readlane_b32 s21, v255, 10
	v_cvt_pk_bf16_f32 v38, v44, v45
	v_mul_f32_e32 v46, v46, v32
	v_sub_f32_e32 v32, v103, v35
	v_mul_f32_e32 v32, 0x3fb8aa3b, v32
	v_exp_f32_e32 v32, v32
	v_readlane_b32 s20, v255, 11
	v_readlane_b32 s21, v255, 12
	s_nop 0
	v_mul_f32_e32 v47, v47, v32
	ds_read_b64_tr_b16 v[32:33], v144
	ds_read_b64_tr_b16 v[34:35], v144 offset:1152
	s_waitcnt lgkmcnt(0)
	v_mfma_f32_32x32x16_bf16 v[16:31], v[32:35], v[40:43], v[16:31]
	ds_read_b64_tr_b16 v[32:33], v144 offset:2304
	ds_read_b64_tr_b16 v[34:35], v144 offset:3456
	v_cvt_pk_bf16_f32 v39, v46, v47
	s_waitcnt lgkmcnt(0)
	s_nop 0
	v_mfma_f32_32x32x16_bf16 v[16:31], v[32:35], v[36:39], v[16:31]
	s_branch .LBB0_110

; #define LAS __attribute__((address_space(3)))
; #define MFMA32(a, b, c) __builtin_amdgcn_mfma_f32_32x32x16_bf16((a), (b), (c), 0, 0, 0)
; __device__ __forceinline__ int crow(int r, int hi) { return (r & 3) + 8 * (r >> 2) + 4 * hi; }
; __device__ __forceinline__ void ssd_item(CP& P, int L, int sq, int hd, int dir, LAS unsigned char* lds) {
;     ...
;             for (int sb = 0; sb < 4; ++sb) if (sb >= sb0 && sb < sb1) {
;                 f32x16 cb;
; #pragma unroll
;                 for (int i = 0; i < 16; ++i) cb[i] = 0.f;
; #pragma unroll
;                 for (int ks = 0; ks < 8; ++ks) { const bf16x8 av = *(const LAS bf16x8*)(lds + S_BM + (32 * sb + r) * SP + (16 * ks + 8 * hi) * 2);
;                     const bf16x8 bv2 = *(const LAS bf16x8*)(lds + S_CM + lrow * SP + (16 * ks + 8 * hi) * 2); cb = MFMA32(av, bv2, cb); }
; #pragma unroll
;                 for (int i = 0; i < 16; ++i) { const int sr = 32 * sb + crow(i, hi); const bool ok = dir ? (sr >= lrow) : (sr <= lrow); const float gv = cb[i] * __expf(a_l - AS[sr]); cb[i] = ok ? gv : 0.f; }
; #pragma unroll
;                 for (int s2 = 0; s2 < 2; ++s2) { const LAS unsigned char* xp = lds + S_XD + (32 * sb + 16 * s2 + 4 * hi + trq) * SXP + 64 * pb + trb;
;                     const s16x4 lo = __builtin_bit_cast(s16x4, __builtin_amdgcn_ds_read_tr16_b64_v4i16((LAS v4i16s_t*)xp));
;                     const s16x4 hi4 = __builtin_bit_cast(s16x4, __builtin_amdgcn_ds_read_tr16_b64_v4i16((LAS v4i16s_t*)(xp + 8 * SXP)));
;                     const bf16x8 xa = __builtin_shufflevector(lo, hi4, 0, 1, 2, 3, 4, 5, 6, 7);
;                     yd = MFMA32(xa, pack_step(cb, s2), yd); }
.LBB0_109:
	ds_read_b128 v[200:203], v151 offset:43520
	ds_read_b128 v[208:211], v152
	ds_read_b128 v[212:215], v151 offset:43552
	ds_read_b128 v[216:219], v152 offset:32
	ds_read_b128 v[220:223], v151 offset:43584
	ds_read_b128 v[246:249], v152 offset:64
	ds_read_b128 v[154:157], v151 offset:43616
	ds_read_b128 v[158:161], v152 offset:96
	v_readlane_b32 s20, v254, 45
	v_readlane_b32 s21, v254, 46
	s_waitcnt lgkmcnt(6)
	v_mfma_f32_32x32x16_bf16 v[32:47], v[200:203], v[208:211], 0
	ds_read_b128 v[200:203], v151 offset:43648
	ds_read_b128 v[208:211], v152 offset:128
	s_waitcnt lgkmcnt(6)
	v_mfma_f32_32x32x16_bf16 v[32:47], v[212:215], v[216:219], v[32:47]
	ds_read_b128 v[212:215], v151 offset:43680
	ds_read_b128 v[216:219], v152 offset:160
	s_waitcnt lgkmcnt(6)
	v_mfma_f32_32x32x16_bf16 v[32:47], v[220:223], v[246:249], v[32:47]
	ds_read_b128 v[220:223], v151 offset:43712
	ds_read_b128 v[246:249], v152 offset:192
	s_waitcnt lgkmcnt(6)
	v_mfma_f32_32x32x16_bf16 v[32:47], v[154:157], v[158:161], v[32:47]
	ds_read_b128 v[154:157], v151 offset:43744
	ds_read_b128 v[158:161], v152 offset:224
	s_waitcnt lgkmcnt(6)
	v_mfma_f32_32x32x16_bf16 v[32:47], v[200:203], v[208:211], v[32:47]
	s_waitcnt lgkmcnt(4)
	v_mfma_f32_32x32x16_bf16 v[32:47], v[212:215], v[216:219], v[32:47]
	s_waitcnt lgkmcnt(2)
	v_mfma_f32_32x32x16_bf16 v[32:47], v[220:223], v[246:249], v[32:47]
	s_waitcnt lgkmcnt(0)
	v_mfma_f32_32x32x16_bf16 v[32:47], v[154:157], v[158:161], v[32:47]
	s_cmp_lg_u32 s32, 1
	s_cbranch_scc1 .Lssd_nm1
	ds_read_b128 v[154:157], v128
	s_waitcnt lgkmcnt(0)
	v_sub_f32_e32 v153, v103, v154
	v_mul_f32_e32 v153, 0x3fb8aa3b, v153
	v_exp_f32_e32 v153, v153
	s_nop 6
	v_mul_f32_e32 v32, v32, v153
	v_cndmask_b32_e64 v153, 0, v32, s[20:21]
	v_sub_f32_e32 v32, v103, v155
	v_mul_f32_e32 v32, 0x3fb8aa3b, v32
	v_exp_f32_e32 v32, v32
	v_readlane_b32 s20, v254, 47
	v_readlane_b32 s21, v254, 48
	v_mul_f32_e32 v32, v33, v32
	s_nop 0
	v_cndmask_b32_e64 v154, 0, v32, s[20:21]
	v_sub_f32_e32 v32, v103, v156
	v_mul_f32_e32 v32, 0x3fb8aa3b, v32
	v_exp_f32_e32 v32, v32
	v_readlane_b32 s20, v254, 49
	v_readlane_b32 s21, v254, 50
	v_mul_f32_e32 v32, v34, v32
	s_nop 0
	v_cndmask_b32_e64 v155, 0, v32, s[20:21]
	v_sub_f32_e32 v32, v103, v157
	v_mul_f32_e32 v32, 0x3fb8aa3b, v32
	v_exp_f32_e32 v32, v32
	v_readlane_b32 s20, v254, 51
	v_readlane_b32 s21, v254, 52
	v_mul_f32_e32 v32, v35, v32
	s_nop 0
	v_cndmask_b32_e64 v156, 0, v32, s[20:21]
	ds_read_b128 v[32:35], v129
	v_readlane_b32 s20, v254, 53
	v_readlane_b32 s21, v254, 54
	s_waitcnt lgkmcnt(0)
	v_sub_f32_e32 v32, v103, v32
	v_mul_f32_e32 v32, 0x3fb8aa3b, v32
	v_exp_f32_e32 v32, v32
	s_nop 0
	v_mul_f32_e32 v32, v36, v32
	v_cndmask_b32_e64 v36, 0, v32, s[20:21]
	v_sub_f32_e32 v32, v103, v33
	v_mul_f32_e32 v32, 0x3fb8aa3b, v32
	v_exp_f32_e32 v32, v32
	v_readlane_b32 s20, v254, 55
	v_readlane_b32 s21, v254, 56
	v_mul_f32_e32 v32, v37, v32
	s_nop 0
	v_cndmask_b32_e64 v37, 0, v32, s[20:21]
	v_sub_f32_e32 v32, v103, v34
	v_mul_f32_e32 v32, 0x3fb8aa3b, v32
	v_exp_f32_e32 v32, v32
	v_readlane_b32 s20, v254, 57
	v_readlane_b32 s21, v254, 58
	v_mul_f32_e32 v32, v38, v32
	s_nop 0
	v_cndmask_b32_e64 v38, 0, v32, s[20:21]
	v_sub_f32_e32 v32, v103, v35
	v_mul_f32_e32 v32, 0x3fb8aa3b, v32
	v_exp_f32_e32 v32, v32
	v_readlane_b32 s20, v254, 59
	v_readlane_b32 s21, v254, 60
	v_mul_f32_e32 v32, v39, v32
	s_nop 0
	v_cndmask_b32_e64 v39, 0, v32, s[20:21]
	ds_read_b128 v[32:35], v130
	v_readlane_b32 s20, v254, 61
	v_readlane_b32 s21, v254, 62
	s_waitcnt lgkmcnt(0)
	v_sub_f32_e32 v32, v103, v32
	v_mul_f32_e32 v32, 0x3fb8aa3b, v32
	v_exp_f32_e32 v32, v32
	s_nop 0
	v_mul_f32_e32 v32, v40, v32
	v_cndmask_b32_e64 v157, 0, v32, s[20:21]
	v_sub_f32_e32 v32, v103, v33
	v_mul_f32_e32 v32, 0x3fb8aa3b, v32
	v_exp_f32_e32 v32, v32
	v_readlane_b32 s20, v254, 63
	v_readlane_b32 s21, v255, 0
	v_cvt_pk_bf16_f32 v40, v153, v154
	v_mul_f32_e32 v32, v41, v32
	v_cndmask_b32_e64 v158, 0, v32, s[20:21]
	v_sub_f32_e32 v32, v103, v34
	v_mul_f32_e32 v32, 0x3fb8aa3b, v32
	v_exp_f32_e32 v32, v32
	v_readlane_b32 s20, v255, 1
	v_readlane_b32 s21, v255, 2
	v_cvt_pk_bf16_f32 v41, v155, v156
	v_mul_f32_e32 v32, v42, v32
	v_cndmask_b32_e64 v159, 0, v32, s[20:21]
	v_sub_f32_e32 v32, v103, v35
	v_mul_f32_e32 v32, 0x3fb8aa3b, v32
	v_exp_f32_e32 v32, v32
	v_readlane_b32 s20, v255, 3
	v_readlane_b32 s21, v255, 4
	v_cvt_pk_bf16_f32 v42, v36, v37
	v_mul_f32_e32 v32, v43, v32
	v_cndmask_b32_e64 v160, 0, v32, s[20:21]
	ds_read_b128 v[32:35], v131
	v_readlane_b32 s20, v255, 5
	v_readlane_b32 s21, v255, 6
	v_cvt_pk_bf16_f32 v43, v38, v39
	v_cvt_pk_bf16_f32 v36, v157, v158
	s_waitcnt lgkmcnt(0)
	v_sub_f32_e32 v32, v103, v32
	v_mul_f32_e32 v32, 0x3fb8aa3b, v32
	v_exp_f32_e32 v32, v32
	v_cvt_pk_bf16_f32 v37, v159, v160
	v_mul_f32_e32 v32, v44, v32
	v_cndmask_b32_e64 v44, 0, v32, s[20:21]
	v_sub_f32_e32 v32, v103, v33
	v_mul_f32_e32 v32, 0x3fb8aa3b, v32
	v_exp_f32_e32 v32, v32
	v_readlane_b32 s20, v255, 7
	v_readlane_b32 s21, v255, 8
	v_mul_f32_e32 v32, v45, v32
	s_nop 0
	v_cndmask_b32_e64 v45, 0, v32, s[20:21]
	v_sub_f32_e32 v32, v103, v34
	v_mul_f32_e32 v32, 0x3fb8aa3b, v32
	v_exp_f32_e32 v32, v32
	v_readlane_b32 s20, v255, 9
	v_readlane_b32 s21, v255, 10
	v_cvt_pk_bf16_f32 v38, v44, v45
	v_mul_f32_e32 v32, v46, v32
	v_cndmask_b32_e64 v46, 0, v32, s[20:21]
	v_sub_f32_e32 v32, v103, v35
	v_mul_f32_e32 v32, 0x3fb8aa3b, v32
	v_exp_f32_e32 v32, v32
	v_readlane_b32 s20, v255, 11
	v_readlane_b32 s21, v255, 12
	v_mul_f32_e32 v32, v47, v32
	s_nop 0
	v_cndmask_b32_e64 v47, 0, v32, s[20:21]
	ds_read_b64_tr_b16 v[32:33], v144
	ds_read_b64_tr_b16 v[34:35], v144 offset:1152
	s_waitcnt lgkmcnt(0)
	v_mfma_f32_32x32x16_bf16 v[16:31], v[32:35], v[40:43], v[16:31]
	ds_read_b64_tr_b16 v[32:33], v144 offset:2304
	ds_read_b64_tr_b16 v[34:35], v144 offset:3456
	v_cvt_pk_bf16_f32 v39, v46, v47
	s_waitcnt lgkmcnt(0)
	s_nop 0
	v_mfma_f32_32x32x16_bf16 v[16:31], v[32:35], v[36:39], v[16:31]
